# back-edge rotation (7.11): loop-back barrier is the attention loop head, counter/exit test and taken branch in front of it, exit path has its own barrier copy
# baseline (speedup 1.0000x reference)
; DI float bf2f(unsigned v) { return __uint_as_float(v << 16); }
; DI f32x16 zero16() { f32x16 z; for (int i = 0; i < 16; ++i) z[i] = 0.f; return z; }
; DI void attn_item(const P& p, int l, int item, char* smem) {
;     ...
;   {
;     float s1 = p.lq1[l * 64 + lane] * p.lk1[l * 64 + lane];
;     float s2 = p.lq2[l * 64 + lane] * p.lk2[l * 64 + lane];
; #pragma unroll
;     for (int m = 32; m >= 1; m >>= 1) { s1 += __shfl_xor(s1, m); s2 += __shfl_xor(s2, m); }
;     lam = __expf(s1) - __expf(s2) + lam_init;
;   }
;   const int tq = qb * 128 + qg * 32 + li;
;   bf16x8 qf[4];
;   float negm;
;   {
;     float q2 = 0.f;
; #pragma unroll
;     for (int ks = 0; ks < 4; ++ks) {
;       qf[ks] = *(const bf16x8*)(p.Qb + ((size_t)((bh * 2 + c) * SEQ + tq)) * 64 + 16 * ks + 8 * g);
; #pragma unroll
;       for (int j = 0; j < 8; ++j) { const float v = bf2f((unsigned)(u16)qf[ks][j]); q2 += v * v; }
;     }
;     q2 += __shfl_xor(q2, 32);
;     const float k2 = __uint_as_float(p.kmax[bh * 2 + c]);
;     negm = -(sqrtf(q2 * k2) * 1.01f + 1e-3f);
;   }
;   f32x16 O[4];
; #pragma unroll
;   for (int eb = 0; eb < 4; ++eb) O[eb] = zero16();
;   float ls = 0.f;
;   u32x4 kreg[2], vreg[2];
;   const u16* kbase = p.Kb + (size_t)(bh * 2) * SEQ * 64;
;   const u16* vbase = p.VT + (size_t)(bh * 128) * VTP;
; #pragma unroll
;   for (int i = 0; i < 2; ++i) kreg[i] = *(const u32x4*)(kbase + ((size_t)i * SEQ) * 64 + tid * 8);
; #pragma unroll
;   for (int i = 0; i < 2; ++i) {
;     const int cid = tid + NT * i;
;     const int e = cid >> 3, kc = cid & 7;
;     vreg[i] = *(const u32x4*)(vbase + (size_t)e * VTP + kc * 8);
;   }
.LBB0_465:
	v_mov_b32_e32 v161, v198
	v_readlane_b32 s6, v248, 26
	v_and_b32_e32 v141, 63, v161
	v_readlane_b32 s72, v248, 30
	v_or_b32_e32 v188, s6, v141
	v_lshlrev_b64 v[0:1], 2, v[188:189]
	v_lshl_add_u64 v[2:3], s[22:23], 0, v[0:1]
	global_load_dword v4, v[2:3], off
	v_lshl_add_u64 v[2:3], s[24:25], 0, v[0:1]
	v_readlane_b32 s73, v248, 31
	global_load_dword v5, v[2:3], off
	v_lshl_add_u64 v[2:3], s[26:27], 0, v[0:1]
	v_lshl_add_u64 v[0:1], s[72:73], 0, v[0:1]
	global_load_dword v2, v[2:3], off
	v_and_b32_e32 v3, 64, v215
	global_load_dword v0, v[0:1], off
	v_add_u32_e32 v3, 64, v3
	v_xor_b32_e32 v7, 32, v215
	v_cmp_lt_i32_e32 vcc, v7, v3
	v_bfe_u32 v162, v161, 6, 2
	s_lshl_b32 s6, s95, 4
	v_cndmask_b32_e32 v7, v215, v7, vcc
	v_lshlrev_b32_e32 v158, 2, v7
	v_ashrrev_i32_e32 v160, 8, v161
	v_and_b32_e32 v17, 31, v161
	s_and_b32 s12, s95, 7
	s_and_b32 s6, s6, 0xffffff80
	v_bfe_u32 v159, v161, 5, 1
	v_lshlrev_b32_e32 v188, 4, v159
	s_and_b32 s13, s64, 7
	s_lshl_b32 s11, s13, 21
	v_mov_b32_e32 v143, v189
	v_ashrrev_i32_e32 v24, 3, v161
	s_movk_i32 s14, 0x4080
	v_mul_lo_u32 v170, v24, s94
	v_mov_b32_e32 v167, 0
	s_mov_b32 s10, 0
	v_mul_u32_u24_e32 v174, 0x90, v17
	v_lshlrev_b32_e32 v8, 5, v162
	v_or3_b32 v140, v8, s6, v17
	s_lshl_b32 s6, s12, 14
	v_lshlrev_b32_e32 v8, 13, v160
	v_add3_u32 v8, v8, s6, v140
	v_ashrrev_i32_e32 v9, 31, v8
	v_lshlrev_b64 v[8:9], 7, v[8:9]
	v_lshl_add_u64 v[8:9], s[38:39], 0, v[8:9]
	v_lshl_add_u64 v[8:9], v[8:9], 0, v[188:189]
	global_load_dwordx4 v[112:115], v[8:9], off
	global_load_dwordx4 v[116:119], v[8:9], off offset:32
	global_load_dwordx4 v[124:127], v[8:9], off offset:64
	global_load_dwordx4 v[120:123], v[8:9], off offset:96
	v_readlane_b32 s6, v248, 38
	v_readlane_b32 s7, v248, 39
	v_lshl_add_u32 v14, s12, 1, v160
	v_ashrrev_i32_e32 v15, 31, v14
	v_lshl_add_u64 v[14:15], v[14:15], 2, s[6:7]
	global_load_dword v14, v[14:15], off
	s_lshl_b32 s6, s12, 21
	s_add_u32 s6, s40, s6
	v_lshlrev_b32_e32 v10, 3, v161
	v_ashrrev_i32_e32 v11, 31, v10
	s_addc_u32 s7, s41, 0
	v_lshlrev_b64 v[32:33], 1, v[10:11]
	v_lshl_add_u64 v[22:23], s[6:7], 0, v[32:33]
	s_mul_i32 s6, s12, 0x204000
	s_add_u32 s6, s42, s6
	v_and_b32_e32 v11, 56, v10
	s_addc_u32 s7, s43, 0
	v_lshlrev_b32_e32 v142, 1, v11
	v_add_u32_e32 v11, 0x200, v161
	v_lshl_add_u64 v[12:13], s[6:7], 0, v[142:143]
	v_ashrrev_i32_e32 v25, 3, v11
	v_mad_i64_i32 v[34:35], s[6:7], v24, s14, 0
	v_mad_i64_i32 v[36:37], s[6:7], v25, s14, 0
	v_mad_i64_i32 v[18:19], s[6:7], v25, s14, v[12:13]
	v_mad_i64_i32 v[20:21], s[6:7], v24, s14, v[12:13]
	s_mov_b32 s6, 0x100000
	s_nop 0
	v_add_co_u32_e32 v8, vcc, s6, v22
	v_and_b32_e32 v26, 48, v10
	v_lshlrev_b32_e32 v10, 2, v161
	v_addc_co_u32_e32 v9, vcc, 0, v23, vcc
	v_and_b32_e32 v27, 4, v10
	global_load_dwordx4 v[80:83], v[18:19], off
	global_load_dwordx4 v[84:87], v[20:21], off
	s_nop 0
	global_load_dwordx4 v[88:91], v[8:9], off
	s_nop 0
	global_load_dwordx4 v[92:95], v[22:23], off
	v_mov_b32_e32 v38, v167
	v_mov_b32_e32 v39, v167
	v_mov_b32_e32 v40, v167
	v_mov_b32_e32 v41, v167
	v_mov_b32_e32 v42, v167
	v_mov_b32_e32 v43, v167
	v_mov_b32_e32 v44, v167
	v_mov_b32_e32 v45, v167
	v_mov_b32_e32 v46, v167
	v_mov_b32_e32 v47, v167
	v_mov_b32_e32 v48, 0
	v_mov_b32_e32 v49, v167
	v_mov_b32_e32 v50, v167
	v_mov_b32_e32 v51, v167
	v_mov_b32_e32 v52, v167
	v_mov_b32_e32 v53, v167
	v_mov_b32_e32 v54, v167
	v_mov_b32_e32 v55, v167
	v_mov_b32_e32 v56, v167
	v_mov_b32_e32 v57, v167
	v_mov_b32_e32 v58, v167
	v_mov_b32_e32 v59, v167
	v_mov_b32_e32 v60, v167
	v_mov_b32_e32 v61, v167
	v_mov_b32_e32 v62, v167
	v_mov_b32_e32 v63, v167
	v_mov_b32_e32 v64, 0
	v_mov_b32_e32 v65, v167
	v_mov_b32_e32 v66, v167
	v_mov_b32_e32 v67, v167
	v_mov_b32_e32 v68, v167
	v_mov_b32_e32 v69, v167
	v_mov_b32_e32 v70, v167
	v_mov_b32_e32 v71, v167
	v_mov_b32_e32 v72, v167
	v_mov_b32_e32 v73, v167
	v_mov_b32_e32 v74, v167
	v_mov_b32_e32 v75, v167
	v_mov_b32_e32 v76, v167
	v_mov_b32_e32 v77, v167
	v_mov_b32_e32 v78, v167
	v_mov_b32_e32 v79, v167
	v_readlane_b32 s74, v248, 32
	v_readlane_b32 s75, v248, 33
	s_waitcnt vmcnt(11)
	v_mul_f32_e32 v6, v4, v5
	ds_bpermute_b32 v6, v158, v6
	s_waitcnt vmcnt(9)
	v_mul_f32_e32 v1, v2, v0
	ds_bpermute_b32 v1, v158, v1
	s_waitcnt lgkmcnt(1)
	v_fmac_f32_e32 v6, v4, v5
	s_waitcnt lgkmcnt(0)
	v_fmac_f32_e32 v1, v2, v0
	v_xor_b32_e32 v0, 16, v215
	v_cmp_lt_i32_e32 vcc, v0, v3
	s_nop 1
	v_cndmask_b32_e32 v0, v215, v0, vcc
	v_lshlrev_b32_e32 v0, 2, v0
	ds_bpermute_b32 v2, v0, v6
	ds_bpermute_b32 v0, v0, v1
	s_waitcnt lgkmcnt(1)
	v_add_f32_e32 v2, v6, v2
	s_waitcnt lgkmcnt(0)
	v_add_f32_e32 v0, v1, v0
	v_xor_b32_e32 v1, 8, v215
	v_cmp_lt_i32_e32 vcc, v1, v3
	s_nop 1
	v_cndmask_b32_e32 v1, v215, v1, vcc
	v_lshlrev_b32_e32 v1, 2, v1
	ds_bpermute_b32 v4, v1, v2
	ds_bpermute_b32 v1, v1, v0
	s_waitcnt lgkmcnt(1)
	v_add_f32_e32 v2, v2, v4
	s_waitcnt lgkmcnt(0)
	v_add_f32_e32 v0, v0, v1
	v_xor_b32_e32 v1, 4, v215
	v_cmp_lt_i32_e32 vcc, v1, v3
	s_nop 1
	v_cndmask_b32_e32 v1, v215, v1, vcc
	v_lshlrev_b32_e32 v1, 2, v1
	ds_bpermute_b32 v4, v1, v2
	ds_bpermute_b32 v1, v1, v0
	s_waitcnt lgkmcnt(1)
	v_add_f32_e32 v2, v2, v4
	s_waitcnt lgkmcnt(0)
	v_add_f32_e32 v0, v0, v1
	v_xor_b32_e32 v1, 2, v215
	v_cmp_lt_i32_e32 vcc, v1, v3
	s_nop 1
	v_cndmask_b32_e32 v1, v215, v1, vcc
	v_lshlrev_b32_e32 v1, 2, v1
	ds_bpermute_b32 v4, v1, v2
	ds_bpermute_b32 v1, v1, v0
	s_waitcnt lgkmcnt(1)
	v_add_f32_e32 v163, v2, v4
	s_waitcnt lgkmcnt(0)
	v_add_f32_e32 v165, v0, v1
	v_xor_b32_e32 v0, 1, v215
	v_cmp_lt_i32_e32 vcc, v0, v3
	s_nop 1
	v_cndmask_b32_e32 v0, v215, v0, vcc
	v_lshlrev_b32_e32 v0, 2, v0
	ds_bpermute_b32 v164, v0, v163
	ds_bpermute_b32 v166, v0, v165
	s_waitcnt vmcnt(8)
; DI float bf2f(unsigned v) { return __uint_as_float(v << 16); }
; DI f32x16 zero16() { f32x16 z; for (int i = 0; i < 16; ++i) z[i] = 0.f; return z; }
; DI void attn_item(const P& p, int l, int item, char* smem) {
;     ...
;     float q2 = 0.f;
; #pragma unroll
;     for (int ks = 0; ks < 4; ++ks) {
;       qf[ks] = *(const bf16x8*)(p.Qb + ((size_t)((bh * 2 + c) * SEQ + tq)) * 64 + 16 * ks + 8 * g);
; #pragma unroll
;       for (int j = 0; j < 8; ++j) { const float v = bf2f((unsigned)(u16)qf[ks][j]); q2 += v * v; }
;     }
;     q2 += __shfl_xor(q2, 32);
;     const float k2 = __uint_as_float(p.kmax[bh * 2 + c]);
;     negm = -(sqrtf(q2 * k2) * 1.01f + 1e-3f);
;   }
;   f32x16 O[4];
; #pragma unroll
;   for (int eb = 0; eb < 4; ++eb) O[eb] = zero16();
;   float ls = 0.f;
;   u32x4 kreg[2], vreg[2];
;   const u16* kbase = p.Kb + (size_t)(bh * 2) * SEQ * 64;
;   const u16* vbase = p.VT + (size_t)(bh * 128) * VTP;
; #pragma unroll
;   for (int i = 0; i < 2; ++i) kreg[i] = *(const u32x4*)(kbase + ((size_t)i * SEQ) * 64 + tid * 8);
; #pragma unroll
;   for (int i = 0; i < 2; ++i) {
;     const int cid = tid + NT * i;
;     const int e = cid >> 3, kc = cid & 7;
;     vreg[i] = *(const u32x4*)(vbase + (size_t)e * VTP + kc * 8);
;   }
;   for (int kt = -1; kt < 128; ++kt) {
;     if (kt + 1 < 128) {
;       u16* Kd = Ks + ((kt + 1) & 1) * (256 * 72);
;       u16* Vd = Kd + 2 * 64 * 72;
; #pragma unroll
;       for (int i = 0; i < 2; ++i) {
;         const int row = tid >> 3, kc = tid & 7;
;         *(u32x4*)(Kd + (i * 64 + row) * 72 + kc * 8) = kreg[i];
;       }
; #pragma unroll
;       for (int i = 0; i < 2; ++i) {
;         const int cid = tid + NT * i;
;         const int e = cid >> 3, kc = cid & 7;
;         uint2 w0; w0.x = vreg[i][0]; w0.y = vreg[i][1];
;         uint2 w1; w1.x = vreg[i][2]; w1.y = vreg[i][3];
;         u16* vd = Vd + e * 72 + (kc >> 1) * 16 + (kc & 1) * 4;
;         *(uint2*)vd = w0;
;         *(uint2*)(vd + 8) = w1;
;       }
;     }
;     if (kt + 2 < 128) {
;       const int kn = kt + 2;
; #pragma unroll
;       for (int i = 0; i < 2; ++i) kreg[i] = *(const u32x4*)(kbase + ((size_t)i * SEQ + kn * 64) * 64 + tid * 8);
; #pragma unroll
;       for (int i = 0; i < 2; ++i) {
;         const int cid = tid + NT * i;
;         const int e = cid >> 3, kc = cid & 7;
;         vreg[i] = *(const u32x4*)(vbase + (size_t)e * VTP + kn * 64 + kc * 8);
;       }
	v_and_b32_e32 v3, 0xffff0000, v112
	v_lshlrev_b32_e32 v2, 16, v112
	v_mul_f32_e32 v3, v3, v3
	v_fmac_f32_e32 v3, v2, v2
	v_lshlrev_b32_e32 v2, 16, v113
	v_fmac_f32_e32 v3, v2, v2
	v_and_b32_e32 v2, 0xffff0000, v113
	v_fmac_f32_e32 v3, v2, v2
	v_lshlrev_b32_e32 v2, 16, v114
	v_fmac_f32_e32 v3, v2, v2
	v_and_b32_e32 v2, 0xffff0000, v114
	v_fmac_f32_e32 v3, v2, v2
	v_lshlrev_b32_e32 v2, 16, v115
	v_fmac_f32_e32 v3, v2, v2
	v_and_b32_e32 v2, 0xffff0000, v115
	v_fmac_f32_e32 v3, v2, v2
	s_waitcnt vmcnt(7)
	v_lshlrev_b32_e32 v2, 16, v116
	v_fmac_f32_e32 v3, v2, v2
	v_and_b32_e32 v2, 0xffff0000, v116
	v_fmac_f32_e32 v3, v2, v2
	v_lshlrev_b32_e32 v2, 16, v117
	v_fmac_f32_e32 v3, v2, v2
	v_and_b32_e32 v2, 0xffff0000, v117
	v_fmac_f32_e32 v3, v2, v2
	v_lshlrev_b32_e32 v2, 16, v118
	v_fmac_f32_e32 v3, v2, v2
	v_and_b32_e32 v2, 0xffff0000, v118
	v_fmac_f32_e32 v3, v2, v2
	v_lshlrev_b32_e32 v2, 16, v119
	v_fmac_f32_e32 v3, v2, v2
	v_and_b32_e32 v2, 0xffff0000, v119
	v_fmac_f32_e32 v3, v2, v2
	s_waitcnt vmcnt(6)
	v_lshlrev_b32_e32 v2, 16, v124
	v_fmac_f32_e32 v3, v2, v2
	v_and_b32_e32 v2, 0xffff0000, v124
	v_fmac_f32_e32 v3, v2, v2
	v_lshlrev_b32_e32 v2, 16, v125
	v_fmac_f32_e32 v3, v2, v2
	v_and_b32_e32 v2, 0xffff0000, v125
	v_fmac_f32_e32 v3, v2, v2
	v_lshlrev_b32_e32 v2, 16, v126
	v_fmac_f32_e32 v3, v2, v2
	v_and_b32_e32 v2, 0xffff0000, v126
	v_fmac_f32_e32 v3, v2, v2
	v_lshlrev_b32_e32 v2, 16, v127
	v_fmac_f32_e32 v3, v2, v2
	v_and_b32_e32 v2, 0xffff0000, v127
	v_fmac_f32_e32 v3, v2, v2
	s_waitcnt vmcnt(5)
	v_lshlrev_b32_e32 v0, 16, v120
	v_fmac_f32_e32 v3, v0, v0
	v_and_b32_e32 v0, 0xffff0000, v120
	v_fmac_f32_e32 v3, v0, v0
	v_and_b32_e32 v1, 0xffff0000, v121
	v_lshlrev_b32_e32 v0, 16, v121
	v_pk_mul_f32 v[0:1], v[0:1], v[0:1]
	s_nop 0
	v_add_f32_e32 v0, v0, v3
	v_add_f32_e32 v2, v1, v0
	v_and_b32_e32 v1, 0xffff0000, v122
	v_lshlrev_b32_e32 v0, 16, v122
	v_pk_mul_f32 v[0:1], v[0:1], v[0:1]
	s_nop 0
	v_add_f32_e32 v0, v0, v2
	v_add_f32_e32 v2, v1, v0
	v_and_b32_e32 v1, 0xffff0000, v123
	v_lshlrev_b32_e32 v0, 16, v123
	v_pk_mul_f32 v[0:1], v[0:1], v[0:1]
	s_nop 0
	v_add_f32_e32 v0, v0, v2
	v_add_f32_e32 v0, v1, v0
	ds_bpermute_b32 v1, v158, v0
	s_waitcnt lgkmcnt(0)
	v_add_f32_e32 v2, v0, v1
	s_mov_b32 s6, 0xf800000
	s_waitcnt vmcnt(4)
	v_mul_f32_e32 v0, v14, v2
	v_cmp_gt_f32_e32 vcc, s6, v0
	v_mul_f32_e32 v1, 0x4f800000, v0
	s_nop 0
	v_cndmask_b32_e32 v0, v0, v1, vcc
	v_sqrt_f32_e32 v1, v0
	s_nop 0
	v_add_u32_e32 v2, -1, v1
	v_fma_f32 v3, -v2, v1, v0
	v_cmp_ge_f32_e64 s[6:7], 0, v3
	v_add_u32_e32 v3, 1, v1
	s_nop 0
	v_cndmask_b32_e64 v2, v1, v2, s[6:7]
	v_fma_f32 v1, -v3, v1, v0
	v_cmp_lt_f32_e64 s[6:7], 0, v1
	s_nop 1
	v_cndmask_b32_e64 v1, v2, v3, s[6:7]
	v_mul_f32_e32 v2, 0x37800000, v1
	v_cndmask_b32_e32 v1, v1, v2, vcc
	v_cmp_class_f32_e32 vcc, v0, v208
	s_nop 0
	s_nop 0
	v_cndmask_b32_e32 v0, v1, v0, vcc
	v_fmamk_f32 v2, v0, 0x3f8147ae, v209
	v_xor_b32_e32 v16, 0x80000000, v2
	v_add_u32_e32 v28, 0, v142
	v_add_u32_e32 v168, v28, v170
	v_lshlrev_b32_e32 v171, 1, v26
	v_lshlrev_b32_e32 v172, 1, v27
	s_waitcnt vmcnt(0)
	ds_write_b128 v168, v[92:95]
	ds_write_b128 v168, v[88:91] offset:9216
	v_add3_u32 v8, 0, v171, v172
	v_add_u32_e32 v169, v8, v170
	v_mul_lo_u32 v173, v25, s94
	v_add_u32_e32 v9, 0x4800, v169
	v_add_u32_e32 v143, v8, v173
	ds_write2_b64 v9, v[84:85], v[86:87] offset1:2
	v_add_u32_e32 v4, 0x4800, v143
	ds_write2_b64 v4, v[80:81], v[82:83] offset1:2
	v_add_co_u32_e32 v0, vcc, s65, v22
	s_mov_b32 s6, 0x102000
	s_nop 0
	v_addc_co_u32_e32 v1, vcc, 0, v23, vcc
	global_load_dwordx4 v[228:231], v[0:1], off
	v_add_co_u32_e32 v0, vcc, s6, v22
	v_lshlrev_b32_e32 v2, 4, v161
	s_nop 0
	v_addc_co_u32_e32 v1, vcc, 0, v23, vcc
	global_load_dwordx4 v[232:235], v[0:1], off
	global_load_dwordx4 v[236:239], v[20:21], off offset:128
	global_load_dwordx4 v[240:243], v[18:19], off offset:128
	v_lshl_or_b32 v0, v160, 6, v17
	v_mul_lo_u32 v175, v0, s94
	v_mad_u64_u32 v[0:1], s[6:7], s13, v219, v[36:37]
	v_and_b32_e32 v2, 0x70, v2
	v_or_b32_e32 v0, v0, v2
	v_lshl_add_u64 v[144:145], s[70:71], 0, v[0:1]
	v_mad_u64_u32 v[0:1], s[6:7], s13, v219, v[34:35]
	v_readlane_b32 s6, v248, 42
	s_add_u32 s6, s6, s11
	v_readlane_b32 s7, v248, 43
	v_or_b32_e32 v0, v0, v2
	s_addc_u32 s7, s7, 0
	v_mov_b32_e32 v17, v16
	v_mov_b32_e32 v18, v16
	v_mov_b32_e32 v19, v16
	v_mov_b32_e32 v20, v16
	v_mov_b32_e32 v21, v16
	v_mov_b32_e32 v22, v16
	v_mov_b32_e32 v23, v16
	v_mov_b32_e32 v24, v16
	v_mov_b32_e32 v25, v16
	v_mov_b32_e32 v26, v16
	v_mov_b32_e32 v27, v16
	v_mov_b32_e32 v28, v16
	v_mov_b32_e32 v29, v16
	v_mov_b32_e32 v30, v16
	v_mov_b32_e32 v31, v16
	v_lshl_add_u64 v[146:147], s[70:71], 0, v[0:1]
	v_lshl_add_u64 v[148:149], s[6:7], 0, v[32:33]
	v_mov_b32_e32 v0, 0
	v_mov_b32_e32 v1, v167
	v_mov_b32_e32 v2, v167
	v_mov_b32_e32 v3, v167
	v_mov_b32_e32 v4, v167
	v_mov_b32_e32 v5, v167
	v_mov_b32_e32 v6, v167
	v_mov_b32_e32 v7, v167
	v_mov_b32_e32 v8, v167
	v_mov_b32_e32 v9, v167
	v_mov_b32_e32 v10, v167
	v_mov_b32_e32 v11, v167
	v_mov_b32_e32 v12, v167
	v_mov_b32_e32 v13, v167
	v_mov_b32_e32 v14, v167
	v_mov_b32_e32 v15, v167
	v_mov_b32_e32 v32, 0
	v_mov_b32_e32 v33, v167
	v_mov_b32_e32 v34, v167
	v_mov_b32_e32 v35, v167
	v_mov_b32_e32 v36, v167
	v_mov_b32_e32 v37, v167
	s_waitcnt lgkmcnt(0)
	s_barrier
; DI void attn_item(const P& p, int l, int item, char* smem) {
;     ...
;   for (int kt = -1; kt < 128; ++kt) {
;     if (kt + 1 < 128) {
;       u16* Kd = Ks + ((kt + 1) & 1) * (256 * 72);
;       u16* Vd = Kd + 2 * 64 * 72;
; #pragma unroll
;       for (int i = 0; i < 2; ++i) {
;         const int row = tid >> 3, kc = tid & 7;
;         *(u32x4*)(Kd + (i * 64 + row) * 72 + kc * 8) = kreg[i];
;       }
; #pragma unroll
;       for (int i = 0; i < 2; ++i) {
;         const int cid = tid + NT * i;
;         const int e = cid >> 3, kc = cid & 7;
;         uint2 w0; w0.x = vreg[i][0]; w0.y = vreg[i][1];
;         uint2 w1; w1.x = vreg[i][2]; w1.y = vreg[i][3];
;         u16* vd = Vd + e * 72 + (kc >> 1) * 16 + (kc & 1) * 4;
;         *(uint2*)vd = w0;
;         *(uint2*)(vd + 8) = w1;
;       }
;     }
;     if (kt + 2 < 128) {
;       const int kn = kt + 2;
; #pragma unroll
;       for (int i = 0; i < 2; ++i) kreg[i] = *(const u32x4*)(kbase + ((size_t)i * SEQ + kn * 64) * 64 + tid * 8);
; #pragma unroll
;       for (int i = 0; i < 2; ++i) {
;         const int cid = tid + NT * i;
;         const int e = cid >> 3, kc = cid & 7;
;         vreg[i] = *(const u32x4*)(vbase + (size_t)e * VTP + kn * 64 + kc * 8);
;       }
;     }
;     __builtin_amdgcn_sched_barrier(0x38F);
;     if (kt >= 0) {
;       const u16* Kc = Ks + (kt & 1) * (256 * 72);
;       const u16* Vc = Kc + 2 * 64 * 72;
;       bf16x8 kf[8];
; #pragma unroll
;       for (int i = 0; i < 8; ++i)
;         kf[i] = *(const bf16x8*)(Kc + (c * 64 + 32 * (i & 1) + li) * 72 + 16 * (i >> 1) + 8 * g);
;       u32x4 vf[16];
; #pragma unroll
;       for (int i = 0; i < 16; ++i) {
;         const int eb = i & 3, s = (i >> 2) & 1, kb = i >> 3;
;         vf[i] = *(const u32x4*)(Vc + (32 * eb + li) * 72 + 32 * kb + 16 * s + 8 * g);
;       }
;       f32x16 S[2];
; #pragma unroll
;       for (int kb = 0; kb < 2; ++kb)
; #pragma unroll
;         for (int r = 0; r < 16; ++r) S[kb][r] = negm;
; #pragma unroll
;       for (int i = 0; i < 8; ++i) S[i & 1] = MFMA(kf[i], qf[i >> 1], S[i & 1]);
;       u32x4 pk[4];
;       float sum = 0.f;
; #pragma unroll
;       for (int ch = 0; ch < 4; ++ch) {
;         const int kb = ch >> 1, s = ch & 1;
; #pragma unroll
;         for (int j2 = 0; j2 < 4; ++j2) {
;           const float p0 = __builtin_amdgcn_exp2f(S[kb][8 * s + 2 * j2]);
	v_add_u32_e32 v150, v175, v188
	v_add_u32_e32 v151, v174, v188
	s_mov_b32 s10, 0xfff00000
	v_add_co_u32_e32 v156, vcc, s10, v148
	v_add_u32_e32 v151, 0x4800, v151
	s_mov_b64 s[14:15], 0x2000
	v_addc_co_u32_e32 v157, vcc, -1, v149, vcc
	v_mov_b32_e32 v190, 0
	v_mov_b32_e32 v191, 0
	v_mov_b32_e32 v196, 0
	s_movk_i32 s10, 63
	ds_read_b128 v[128:131], v150 offset:0
	ds_read_b128 v[132:135], v150 offset:32
	ds_read_b128 v[136:139], v150 offset:64
	ds_read_b128 v[152:155], v150 offset:96
	ds_read_b128 v[224:227], v150 offset:4608
	ds_read_b128 v[244:247], v150 offset:4640
	s_waitcnt lgkmcnt(4)
	v_mfma_f32_32x32x16_bf16 v[96:111], v[128:131], v[112:115], v[16:31]
	ds_read_b128 v[128:131], v150 offset:4672
	v_mfma_f32_32x32x16_bf16 v[96:111], v[132:135], v[116:119], v[96:111]
	ds_read_b128 v[132:135], v150 offset:4704
	s_waitcnt lgkmcnt(4)
	v_mfma_f32_32x32x16_bf16 v[96:111], v[136:139], v[124:127], v[96:111]
	ds_read_b128 v[136:139], v151 offset:0
	v_mfma_f32_32x32x16_bf16 v[96:111], v[152:155], v[120:123], v[96:111]
	ds_read_b128 v[152:155], v151 offset:4608
	s_waitcnt lgkmcnt(4)
	v_mfma_f32_32x32x16_bf16 v[80:95], v[224:227], v[112:115], v[16:31]
	ds_read_b128 v[224:227], v151 offset:9216
	v_mfma_f32_32x32x16_bf16 v[80:95], v[244:247], v[116:119], v[80:95]
	ds_read_b128 v[244:247], v151 offset:13824
	s_nop 6
	v_exp_f32_e32 v96, v96
	v_exp_f32_e32 v97, v97
	s_waitcnt lgkmcnt(4)
	v_mfma_f32_32x32x16_bf16 v[80:95], v[128:131], v[124:127], v[80:95]
	ds_read_b128 v[128:131], v151 offset:32
	v_exp_f32_e32 v98, v98
	v_exp_f32_e32 v99, v99
	v_exp_f32_e32 v100, v100
	v_mfma_f32_32x32x16_bf16 v[80:95], v[132:135], v[120:123], v[80:95]
	ds_read_b128 v[132:135], v151 offset:4640
	v_exp_f32_e32 v101, v101
	v_exp_f32_e32 v102, v102
	v_exp_f32_e32 v103, v103
	v_add_f32_e32 v167, v167, v96
	v_add_f32_e32 v190, v190, v97
	v_add_f32_e32 v191, v191, v98
	v_cvt_pk_bf16_f32 v176, v96, v97
	v_cvt_pk_bf16_f32 v177, v98, v99
	v_cvt_pk_bf16_f32 v178, v100, v101
	v_cvt_pk_bf16_f32 v179, v102, v103
	v_add_f32_e32 v196, v196, v99
	v_add_f32_e32 v167, v167, v100
	v_add_f32_e32 v190, v190, v101
	v_add_f32_e32 v191, v191, v102
	v_add_f32_e32 v196, v196, v103
	s_branch .Lat_loop
.Lat_head:
	s_barrier
	ds_read_b128 v[128:131], v150 offset:0
	ds_read_b128 v[132:135], v150 offset:32
	ds_read_b128 v[136:139], v150 offset:64
	ds_read_b128 v[152:155], v150 offset:96
	ds_read_b128 v[224:227], v150 offset:4608
	ds_read_b128 v[244:247], v150 offset:4640
	global_load_dwordx4 v[232:235], v[148:149], off
	global_load_dwordx4 v[228:231], v[156:157], off
	global_load_dwordx4 v[236:239], v[146:147], off
	global_load_dwordx4 v[240:243], v[144:145], off
	s_waitcnt lgkmcnt(4)
	v_mfma_f32_32x32x16_bf16 v[96:111], v[128:131], v[112:115], v[16:31]
	ds_read_b128 v[128:131], v150 offset:4672
	v_add_f32_e64 v167, v167, v88
	v_add_f32_e32 v190, v190, v89
	v_mfma_f32_32x32x16_bf16 v[96:111], v[132:135], v[116:119], v[96:111]
	ds_read_b128 v[132:135], v150 offset:4704
	v_add_f32_e64 v191, v191, v90
	v_add_f32_e32 v196, v196, v91
	s_waitcnt lgkmcnt(4)
	v_mfma_f32_32x32x16_bf16 v[96:111], v[136:139], v[124:127], v[96:111]
	ds_read_b128 v[136:139], v151 offset:0
	v_add_f32_e64 v167, v167, v92
	v_add_f32_e64 v190, v190, v93
	v_mfma_f32_32x32x16_bf16 v[96:111], v[152:155], v[120:123], v[96:111]
	ds_read_b128 v[152:155], v151 offset:4608
	v_add_f32_e64 v191, v191, v94
	v_add_f32_e32 v196, v196, v95
	v_lshl_add_u64 v[148:149], v[148:149], 0, s[14:15]
	v_lshl_add_u64 v[156:157], v[156:157], 0, s[14:15]
	s_waitcnt lgkmcnt(4)
	v_mfma_f32_32x32x16_bf16 v[80:95], v[224:227], v[112:115], v[16:31]
	ds_read_b128 v[224:227], v151 offset:9216
	v_lshl_add_u64 v[146:147], v[146:147], 0, s[58:59]
	v_lshl_add_u64 v[144:145], v[144:145], 0, s[58:59]
	v_mfma_f32_32x32x16_bf16 v[80:95], v[244:247], v[116:119], v[80:95]
	ds_read_b128 v[244:247], v151 offset:13824
	s_nop 2
	v_exp_f32_e64 v96, v96
	v_exp_f32_e64 v97, v97
	s_waitcnt lgkmcnt(4)
	v_mfma_f32_32x32x16_bf16 v[80:95], v[128:131], v[124:127], v[80:95]
	ds_read_b128 v[128:131], v151 offset:32
	v_exp_f32_e64 v98, v98
	v_exp_f32_e64 v99, v99
	v_exp_f32_e64 v100, v100
	v_mfma_f32_32x32x16_bf16 v[80:95], v[132:135], v[120:123], v[80:95]
	ds_read_b128 v[132:135], v151 offset:4640
	v_exp_f32_e64 v101, v101
	v_exp_f32_e64 v102, v102
	v_exp_f32_e64 v103, v103
	v_add_f32_e64 v167, v167, v96
	v_add_f32_e64 v190, v190, v97
	v_add_f32_e64 v191, v191, v98
	v_cvt_pk_bf16_f32 v176, v96, v97
	v_cvt_pk_bf16_f32 v177, v98, v99
	v_cvt_pk_bf16_f32 v178, v100, v101
	v_cvt_pk_bf16_f32 v179, v102, v103
	v_add_f32_e64 v196, v196, v99
	v_add_f32_e64 v167, v167, v100
	v_add_f32_e64 v190, v190, v101
	v_add_f32_e64 v191, v191, v102
	v_add_f32_e32 v196, v196, v103
; #define MFMA(a, b, c) __builtin_amdgcn_mfma_f32_32x32x16_bf16((a), (b), (c), 0, 0, 0)
; DI void attn_item(const P& p, int l, int item, char* smem) {
;     ...
;     if (kt >= 0) {
;       const u16* Kc = Ks + (kt & 1) * (256 * 72);
;       const u16* Vc = Kc + 2 * 64 * 72;
;       bf16x8 kf[8];
; #pragma unroll
;       for (int i = 0; i < 8; ++i)
;         kf[i] = *(const bf16x8*)(Kc + (c * 64 + 32 * (i & 1) + li) * 72 + 16 * (i >> 1) + 8 * g);
;       u32x4 vf[16];
; #pragma unroll
;       for (int i = 0; i < 16; ++i) {
;         const int eb = i & 3, s = (i >> 2) & 1, kb = i >> 3;
;         vf[i] = *(const u32x4*)(Vc + (32 * eb + li) * 72 + 32 * kb + 16 * s + 8 * g);
;       }
;       f32x16 S[2];
; #pragma unroll
;       for (int kb = 0; kb < 2; ++kb)
; #pragma unroll
;         for (int r = 0; r < 16; ++r) S[kb][r] = negm;
; #pragma unroll
;       for (int i = 0; i < 8; ++i) S[i & 1] = MFMA(kf[i], qf[i >> 1], S[i & 1]);
;       u32x4 pk[4];
;       float sum = 0.f;
; #pragma unroll
;       for (int ch = 0; ch < 4; ++ch) {
;         const int kb = ch >> 1, s = ch & 1;
; #pragma unroll
;         for (int j2 = 0; j2 < 4; ++j2) {
;           const float p0 = __builtin_amdgcn_exp2f(S[kb][8 * s + 2 * j2]);
;           const float p1 = __builtin_amdgcn_exp2f(S[kb][8 * s + 2 * j2 + 1]);
;           sum += p0 + p1;
;           pk[ch][j2] = pack2(p0, p1);
;         }
;       }
;       ls += sum;
; #pragma unroll
;       for (int i = 0; i < 16; ++i) {
;         const int eb = i & 3, ch = i >> 2;
;         O[eb] = MFMA(__builtin_bit_cast(bf16x8, vf[i]), __builtin_bit_cast(bf16x8, pk[ch]), O[eb]);
;       }
;     }
;     __syncthreads();
.Lat_loop:
	s_waitcnt lgkmcnt(4)
	v_mfma_f32_32x32x16_bf16 v[64:79], v[136:139], v[176:179], v[64:79]
	ds_read_b128 v[136:139], v151 offset:9248
	v_exp_f32_e64 v104, v104
	v_exp_f32_e64 v105, v105
	v_mfma_f32_32x32x16_bf16 v[48:63], v[152:155], v[176:179], v[48:63]
	ds_read_b128 v[152:155], v151 offset:13856
	v_exp_f32_e64 v106, v106
	v_exp_f32_e32 v107, v107
	v_cvt_pk_bf16_f32 v180, v104, v105
	s_waitcnt lgkmcnt(4)
	v_mfma_f32_32x32x16_bf16 v[32:47], v[224:227], v[176:179], v[32:47]
	ds_read_b128 v[224:227], v151 offset:64
	v_exp_f32_e64 v108, v108
	v_exp_f32_e64 v109, v109
	v_cvt_pk_bf16_f32 v181, v106, v107
	v_mfma_f32_32x32x16_bf16 v[0:15], v[244:247], v[176:179], v[0:15]
	ds_read_b128 v[244:247], v151 offset:4672
	v_exp_f32_e64 v110, v110
	v_exp_f32_e64 v111, v111
	v_cvt_pk_bf16_f32 v182, v108, v109
	v_cvt_pk_bf16_f32 v183, v110, v111
	s_nop 0
	s_waitcnt lgkmcnt(4)
	v_mfma_f32_32x32x16_bf16 v[64:79], v[128:131], v[180:183], v[64:79]
	ds_read_b128 v[128:131], v151 offset:9280
	v_exp_f32_e64 v80, v80
	v_exp_f32_e64 v81, v81
	v_mfma_f32_32x32x16_bf16 v[48:63], v[132:135], v[180:183], v[48:63]
	ds_read_b128 v[132:135], v151 offset:13888
	v_exp_f32_e64 v82, v82
	v_exp_f32_e32 v83, v83
	v_cvt_pk_bf16_f32 v184, v80, v81
	s_waitcnt lgkmcnt(4)
	v_mfma_f32_32x32x16_bf16 v[32:47], v[136:139], v[180:183], v[32:47]
	ds_read_b128 v[136:139], v151 offset:96
	v_exp_f32_e64 v84, v84
	v_exp_f32_e64 v85, v85
	v_cvt_pk_bf16_f32 v185, v82, v83
	v_mfma_f32_32x32x16_bf16 v[0:15], v[152:155], v[180:183], v[0:15]
	ds_read_b128 v[152:155], v151 offset:4704
	v_exp_f32_e64 v86, v86
	v_exp_f32_e64 v87, v87
	v_cvt_pk_bf16_f32 v186, v84, v85
	v_cvt_pk_bf16_f32 v187, v86, v87
	s_nop 0
	s_waitcnt lgkmcnt(4)
	v_mfma_f32_32x32x16_bf16 v[64:79], v[224:227], v[184:187], v[64:79]
	ds_read_b128 v[224:227], v151 offset:9312
	v_exp_f32_e64 v88, v88
	v_exp_f32_e64 v89, v89
	v_mfma_f32_32x32x16_bf16 v[48:63], v[244:247], v[184:187], v[48:63]
	ds_read_b128 v[244:247], v151 offset:13920
	v_exp_f32_e64 v90, v90
	v_exp_f32_e32 v91, v91
	v_cvt_pk_bf16_f32 v192, v88, v89
	s_waitcnt lgkmcnt(4)
	v_mfma_f32_32x32x16_bf16 v[32:47], v[128:131], v[184:187], v[32:47]
	v_exp_f32_e64 v92, v92
	v_exp_f32_e32 v93, v93
	v_cvt_pk_bf16_f32 v193, v90, v91
	s_waitcnt vmcnt(0)
	ds_write_b128 v168, v[228:231] offset:36864
	ds_write_b128 v168, v[232:235] offset:46080
	v_mfma_f32_32x32x16_bf16 v[0:15], v[132:135], v[184:187], v[0:15]
	v_exp_f32_e64 v94, v94
	v_exp_f32_e32 v95, v95
	v_cvt_pk_bf16_f32 v194, v92, v93
	v_cvt_pk_bf16_f32 v195, v94, v95
	s_nop 0
	ds_write_b64 v169, v[236:237] offset:55296
	ds_write_b64 v169, v[238:239] offset:55312
	s_waitcnt lgkmcnt(6)
	v_mfma_f32_32x32x16_bf16 v[64:79], v[136:139], v[192:195], v[64:79]
	v_add_f32_e64 v167, v167, v104
	v_add_f32_e64 v190, v190, v105
	v_add_f32_e64 v191, v191, v106
	v_add_f32_e32 v196, v196, v107
	ds_write_b64 v143, v[240:241] offset:55296
	ds_write_b64 v143, v[242:243] offset:55312
	v_mfma_f32_32x32x16_bf16 v[48:63], v[152:155], v[192:195], v[48:63]
	v_add_f32_e64 v167, v167, v108
	v_add_f32_e64 v190, v190, v109
	v_add_f32_e64 v191, v191, v110
	v_add_f32_e32 v196, v196, v111
	s_waitcnt lgkmcnt(6)
	v_mfma_f32_32x32x16_bf16 v[32:47], v[224:227], v[192:195], v[32:47]
	v_add_f32_e64 v167, v167, v80
	v_add_f32_e64 v190, v190, v81
	v_add_f32_e64 v191, v191, v82
	v_add_f32_e64 v196, v196, v83
	v_mfma_f32_32x32x16_bf16 v[0:15], v[244:247], v[192:195], v[0:15]
	v_add_f32_e64 v167, v167, v84
	v_add_f32_e64 v190, v190, v85
	v_add_f32_e64 v191, v191, v86
	v_add_f32_e64 v196, v196, v87
	s_waitcnt lgkmcnt(0)
	s_barrier
	ds_read_b128 v[128:131], v150 offset:36864
	ds_read_b128 v[132:135], v150 offset:36896
	ds_read_b128 v[136:139], v150 offset:36928
	ds_read_b128 v[152:155], v150 offset:36960
	ds_read_b128 v[224:227], v150 offset:41472
	ds_read_b128 v[244:247], v150 offset:41504
	global_load_dwordx4 v[232:235], v[148:149], off
	global_load_dwordx4 v[228:231], v[156:157], off
	global_load_dwordx4 v[236:239], v[146:147], off
	global_load_dwordx4 v[240:243], v[144:145], off
	s_waitcnt lgkmcnt(4)
	v_mfma_f32_32x32x16_bf16 v[96:111], v[128:131], v[112:115], v[16:31]
	ds_read_b128 v[128:131], v150 offset:41536
	v_add_f32_e64 v167, v167, v88
	v_add_f32_e32 v190, v190, v89
	v_mfma_f32_32x32x16_bf16 v[96:111], v[132:135], v[116:119], v[96:111]
	ds_read_b128 v[132:135], v150 offset:41568
	v_add_f32_e64 v191, v191, v90
	v_add_f32_e32 v196, v196, v91
	s_waitcnt lgkmcnt(4)
	v_mfma_f32_32x32x16_bf16 v[96:111], v[136:139], v[124:127], v[96:111]
	ds_read_b128 v[136:139], v151 offset:36864
	v_add_f32_e64 v167, v167, v92
	v_add_f32_e64 v190, v190, v93
	v_mfma_f32_32x32x16_bf16 v[96:111], v[152:155], v[120:123], v[96:111]
	ds_read_b128 v[152:155], v151 offset:41472
	v_add_f32_e64 v191, v191, v94
	v_add_f32_e32 v196, v196, v95
	v_lshl_add_u64 v[148:149], v[148:149], 0, s[14:15]
	v_lshl_add_u64 v[156:157], v[156:157], 0, s[14:15]
	s_waitcnt lgkmcnt(4)
	v_mfma_f32_32x32x16_bf16 v[80:95], v[224:227], v[112:115], v[16:31]
	ds_read_b128 v[224:227], v151 offset:46080
	v_lshl_add_u64 v[146:147], v[146:147], 0, s[58:59]
	v_lshl_add_u64 v[144:145], v[144:145], 0, s[58:59]
	v_mfma_f32_32x32x16_bf16 v[80:95], v[244:247], v[116:119], v[80:95]
	ds_read_b128 v[244:247], v151 offset:50688
	s_nop 2
	v_exp_f32_e64 v96, v96
	v_exp_f32_e64 v97, v97
	s_waitcnt lgkmcnt(4)
; #define MFMA(a, b, c) __builtin_amdgcn_mfma_f32_32x32x16_bf16((a), (b), (c), 0, 0, 0)
; DI void attn_item(const P& p, int l, int item, char* smem) {
;     ...
;     if (kt >= 0) {
;       const u16* Kc = Ks + (kt & 1) * (256 * 72);
;       const u16* Vc = Kc + 2 * 64 * 72;
;       bf16x8 kf[8];
; #pragma unroll
;       for (int i = 0; i < 8; ++i)
;         kf[i] = *(const bf16x8*)(Kc + (c * 64 + 32 * (i & 1) + li) * 72 + 16 * (i >> 1) + 8 * g);
;       u32x4 vf[16];
; #pragma unroll
;       for (int i = 0; i < 16; ++i) {
;         const int eb = i & 3, s = (i >> 2) & 1, kb = i >> 3;
;         vf[i] = *(const u32x4*)(Vc + (32 * eb + li) * 72 + 32 * kb + 16 * s + 8 * g);
;       }
;       f32x16 S[2];
; #pragma unroll
;       for (int kb = 0; kb < 2; ++kb)
; #pragma unroll
;         for (int r = 0; r < 16; ++r) S[kb][r] = negm;
; #pragma unroll
;       for (int i = 0; i < 8; ++i) S[i & 1] = MFMA(kf[i], qf[i >> 1], S[i & 1]);
;       u32x4 pk[4];
;       float sum = 0.f;
; #pragma unroll
;       for (int ch = 0; ch < 4; ++ch) {
;         const int kb = ch >> 1, s = ch & 1;
; #pragma unroll
;         for (int j2 = 0; j2 < 4; ++j2) {
;           const float p0 = __builtin_amdgcn_exp2f(S[kb][8 * s + 2 * j2]);
;           const float p1 = __builtin_amdgcn_exp2f(S[kb][8 * s + 2 * j2 + 1]);
;           sum += p0 + p1;
;           pk[ch][j2] = pack2(p0, p1);
;         }
;       }
;       ls += sum;
; #pragma unroll
;       for (int i = 0; i < 16; ++i) {
;         const int eb = i & 3, ch = i >> 2;
;         O[eb] = MFMA(__builtin_bit_cast(bf16x8, vf[i]), __builtin_bit_cast(bf16x8, pk[ch]), O[eb]);
;       }
;     }
;     __syncthreads();
	v_mfma_f32_32x32x16_bf16 v[80:95], v[128:131], v[124:127], v[80:95]
	ds_read_b128 v[128:131], v151 offset:36896
	v_exp_f32_e64 v98, v98
	v_exp_f32_e64 v99, v99
	v_exp_f32_e64 v100, v100
	v_mfma_f32_32x32x16_bf16 v[80:95], v[132:135], v[120:123], v[80:95]
	ds_read_b128 v[132:135], v151 offset:41504
	v_exp_f32_e64 v101, v101
	v_exp_f32_e64 v102, v102
	v_exp_f32_e64 v103, v103
	v_add_f32_e64 v167, v167, v96
	v_add_f32_e64 v190, v190, v97
	v_add_f32_e64 v191, v191, v98
	v_cvt_pk_bf16_f32 v176, v96, v97
	v_cvt_pk_bf16_f32 v177, v98, v99
	v_cvt_pk_bf16_f32 v178, v100, v101
	v_cvt_pk_bf16_f32 v179, v102, v103
	v_add_f32_e64 v196, v196, v99
	v_add_f32_e64 v167, v167, v100
	v_add_f32_e64 v190, v190, v101
	v_add_f32_e64 v191, v191, v102
	v_add_f32_e32 v196, v196, v103
	s_waitcnt lgkmcnt(4)
	v_mfma_f32_32x32x16_bf16 v[64:79], v[136:139], v[176:179], v[64:79]
	ds_read_b128 v[136:139], v151 offset:46112
	v_exp_f32_e64 v104, v104
	v_exp_f32_e64 v105, v105
	v_mfma_f32_32x32x16_bf16 v[48:63], v[152:155], v[176:179], v[48:63]
	ds_read_b128 v[152:155], v151 offset:50720
	v_exp_f32_e64 v106, v106
	v_exp_f32_e32 v107, v107
	v_cvt_pk_bf16_f32 v180, v104, v105
	s_waitcnt lgkmcnt(4)
	v_mfma_f32_32x32x16_bf16 v[32:47], v[224:227], v[176:179], v[32:47]
	ds_read_b128 v[224:227], v151 offset:36928
	v_exp_f32_e64 v108, v108
	v_exp_f32_e64 v109, v109
	v_cvt_pk_bf16_f32 v181, v106, v107
	v_mfma_f32_32x32x16_bf16 v[0:15], v[244:247], v[176:179], v[0:15]
	ds_read_b128 v[244:247], v151 offset:41536
	v_exp_f32_e64 v110, v110
	v_exp_f32_e64 v111, v111
	v_cvt_pk_bf16_f32 v182, v108, v109
	v_cvt_pk_bf16_f32 v183, v110, v111
	s_nop 0
	s_waitcnt lgkmcnt(4)
	v_mfma_f32_32x32x16_bf16 v[64:79], v[128:131], v[180:183], v[64:79]
	ds_read_b128 v[128:131], v151 offset:46144
	v_exp_f32_e64 v80, v80
	v_exp_f32_e64 v81, v81
	v_mfma_f32_32x32x16_bf16 v[48:63], v[132:135], v[180:183], v[48:63]
	ds_read_b128 v[132:135], v151 offset:50752
	v_exp_f32_e64 v82, v82
	v_exp_f32_e32 v83, v83
	v_cvt_pk_bf16_f32 v184, v80, v81
	s_waitcnt lgkmcnt(4)
	v_mfma_f32_32x32x16_bf16 v[32:47], v[136:139], v[180:183], v[32:47]
	ds_read_b128 v[136:139], v151 offset:36960
	v_exp_f32_e64 v84, v84
	v_exp_f32_e64 v85, v85
	v_cvt_pk_bf16_f32 v185, v82, v83
	v_mfma_f32_32x32x16_bf16 v[0:15], v[152:155], v[180:183], v[0:15]
	ds_read_b128 v[152:155], v151 offset:41568
	v_exp_f32_e64 v86, v86
	v_exp_f32_e64 v87, v87
	v_cvt_pk_bf16_f32 v186, v84, v85
	v_cvt_pk_bf16_f32 v187, v86, v87
	s_nop 0
	s_waitcnt lgkmcnt(4)
	v_mfma_f32_32x32x16_bf16 v[64:79], v[224:227], v[184:187], v[64:79]
	ds_read_b128 v[224:227], v151 offset:46176
	v_exp_f32_e64 v88, v88
	v_exp_f32_e64 v89, v89
	v_mfma_f32_32x32x16_bf16 v[48:63], v[244:247], v[184:187], v[48:63]
	ds_read_b128 v[244:247], v151 offset:50784
	v_exp_f32_e64 v90, v90
	v_exp_f32_e32 v91, v91
	v_cvt_pk_bf16_f32 v192, v88, v89
	s_waitcnt lgkmcnt(4)
	v_mfma_f32_32x32x16_bf16 v[32:47], v[128:131], v[184:187], v[32:47]
	v_exp_f32_e64 v92, v92
	v_exp_f32_e32 v93, v93
	v_cvt_pk_bf16_f32 v193, v90, v91
	s_waitcnt vmcnt(0)
	ds_write_b128 v168, v[228:231] offset:0
	ds_write_b128 v168, v[232:235] offset:9216
	v_mfma_f32_32x32x16_bf16 v[0:15], v[132:135], v[184:187], v[0:15]
	v_exp_f32_e64 v94, v94
	v_exp_f32_e32 v95, v95
	v_cvt_pk_bf16_f32 v194, v92, v93
	v_cvt_pk_bf16_f32 v195, v94, v95
	s_nop 0
	ds_write_b64 v169, v[236:237] offset:18432
	ds_write_b64 v169, v[238:239] offset:18448
	s_waitcnt lgkmcnt(6)
	v_mfma_f32_32x32x16_bf16 v[64:79], v[136:139], v[192:195], v[64:79]
	v_add_f32_e64 v167, v167, v104
	v_add_f32_e64 v190, v190, v105
	v_add_f32_e64 v191, v191, v106
	v_add_f32_e32 v196, v196, v107
	ds_write_b64 v143, v[240:241] offset:18432
	ds_write_b64 v143, v[242:243] offset:18448
	v_mfma_f32_32x32x16_bf16 v[48:63], v[152:155], v[192:195], v[48:63]
	v_add_f32_e64 v167, v167, v108
	v_add_f32_e64 v190, v190, v109
	v_add_f32_e64 v191, v191, v110
	v_add_f32_e32 v196, v196, v111
	s_waitcnt lgkmcnt(6)
	v_mfma_f32_32x32x16_bf16 v[32:47], v[224:227], v[192:195], v[32:47]
	v_add_f32_e64 v167, v167, v80
	v_add_f32_e64 v190, v190, v81
	v_add_f32_e64 v191, v191, v82
	v_add_f32_e64 v196, v196, v83
	v_mfma_f32_32x32x16_bf16 v[0:15], v[244:247], v[192:195], v[0:15]
	v_add_f32_e64 v167, v167, v84
	v_add_f32_e64 v190, v190, v85
	v_add_f32_e64 v191, v191, v86
	v_add_f32_e64 v196, v196, v87
	s_waitcnt lgkmcnt(0)
	s_add_i32 s10, s10, -1
	s_cmp_eq_u32 s10, 0
	s_cbranch_scc1 .Lat_exit
	s_branch .Lat_head
; DI void attn_item(const P& p, int l, int item, char* smem) {
;     ...
;   for (int kt = -1; kt < 128; ++kt) {
;     if (kt + 1 < 128) {
;       u16* Kd = Ks + ((kt + 1) & 1) * (256 * 72);
;       u16* Vd = Kd + 2 * 64 * 72;
; #pragma unroll
;       for (int i = 0; i < 2; ++i) {
;         const int row = tid >> 3, kc = tid & 7;
;         *(u32x4*)(Kd + (i * 64 + row) * 72 + kc * 8) = kreg[i];
;       }
; #pragma unroll
;       for (int i = 0; i < 2; ++i) {
;         const int cid = tid + NT * i;
;         const int e = cid >> 3, kc = cid & 7;
;         uint2 w0; w0.x = vreg[i][0]; w0.y = vreg[i][1];
;         uint2 w1; w1.x = vreg[i][2]; w1.y = vreg[i][3];
;         u16* vd = Vd + e * 72 + (kc >> 1) * 16 + (kc & 1) * 4;
;         *(uint2*)vd = w0;
;         *(uint2*)(vd + 8) = w1;
;       }
;     }
;     if (kt + 2 < 128) {
;       const int kn = kt + 2;
; #pragma unroll
;       for (int i = 0; i < 2; ++i) kreg[i] = *(const u32x4*)(kbase + ((size_t)i * SEQ + kn * 64) * 64 + tid * 8);
; #pragma unroll
;       for (int i = 0; i < 2; ++i) {
;         const int cid = tid + NT * i;
;         const int e = cid >> 3, kc = cid & 7;
;         vreg[i] = *(const u32x4*)(vbase + (size_t)e * VTP + kn * 64 + kc * 8);
;       }
;     }
;     __builtin_amdgcn_sched_barrier(0x38F);
;     if (kt >= 0) {
;       const u16* Kc = Ks + (kt & 1) * (256 * 72);
;       const u16* Vc = Kc + 2 * 64 * 72;
;       bf16x8 kf[8];
; #pragma unroll
;       for (int i = 0; i < 8; ++i)
;         kf[i] = *(const bf16x8*)(Kc + (c * 64 + 32 * (i & 1) + li) * 72 + 16 * (i >> 1) + 8 * g);
;       u32x4 vf[16];
; #pragma unroll
;       for (int i = 0; i < 16; ++i) {
;         const int eb = i & 3, s = (i >> 2) & 1, kb = i >> 3;
;         vf[i] = *(const u32x4*)(Vc + (32 * eb + li) * 72 + 32 * kb + 16 * s + 8 * g);
;       }
;       f32x16 S[2];
; #pragma unroll
;       for (int kb = 0; kb < 2; ++kb)
; #pragma unroll
;         for (int r = 0; r < 16; ++r) S[kb][r] = negm;
; #pragma unroll
;       for (int i = 0; i < 8; ++i) S[i & 1] = MFMA(kf[i], qf[i >> 1], S[i & 1]);
;       u32x4 pk[4];
;       float sum = 0.f;
; #pragma unroll
;       for (int ch = 0; ch < 4; ++ch) {
;         const int kb = ch >> 1, s = ch & 1;
; #pragma unroll
;         for (int j2 = 0; j2 < 4; ++j2) {
;           const float p0 = __builtin_amdgcn_exp2f(S[kb][8 * s + 2 * j2]);
.Lat_exit:
	s_barrier
	ds_read_b128 v[128:131], v150 offset:0
	ds_read_b128 v[132:135], v150 offset:32
	ds_read_b128 v[136:139], v150 offset:64
	ds_read_b128 v[152:155], v150 offset:96
	ds_read_b128 v[224:227], v150 offset:4608
	ds_read_b128 v[244:247], v150 offset:4640
	global_load_dwordx4 v[232:235], v[148:149], off
	global_load_dwordx4 v[228:231], v[156:157], off
	global_load_dwordx4 v[236:239], v[146:147], off
	global_load_dwordx4 v[240:243], v[144:145], off
	s_waitcnt lgkmcnt(4)
	v_mfma_f32_32x32x16_bf16 v[96:111], v[128:131], v[112:115], v[16:31]
	ds_read_b128 v[128:131], v150 offset:4672
	v_add_f32_e32 v167, v167, v88
	v_add_f32_e32 v190, v190, v89
	v_mfma_f32_32x32x16_bf16 v[96:111], v[132:135], v[116:119], v[96:111]
	ds_read_b128 v[132:135], v150 offset:4704
	v_add_f32_e32 v191, v191, v90
	v_add_f32_e32 v196, v196, v91
	s_waitcnt lgkmcnt(4)
	v_mfma_f32_32x32x16_bf16 v[96:111], v[136:139], v[124:127], v[96:111]
	ds_read_b128 v[136:139], v151 offset:0
	v_add_f32_e32 v167, v167, v92
	v_add_f32_e32 v190, v190, v93
	v_mfma_f32_32x32x16_bf16 v[96:111], v[152:155], v[120:123], v[96:111]
	ds_read_b128 v[152:155], v151 offset:4608
	v_add_f32_e32 v191, v191, v94
	v_add_f32_e32 v196, v196, v95
	v_lshl_add_u64 v[148:149], v[148:149], 0, s[14:15]
	v_lshl_add_u64 v[156:157], v[156:157], 0, s[14:15]
	s_waitcnt lgkmcnt(4)
	v_mfma_f32_32x32x16_bf16 v[80:95], v[224:227], v[112:115], v[16:31]
	ds_read_b128 v[224:227], v151 offset:9216
	v_lshl_add_u64 v[146:147], v[146:147], 0, s[58:59]
	v_lshl_add_u64 v[144:145], v[144:145], 0, s[58:59]
	v_mfma_f32_32x32x16_bf16 v[80:95], v[244:247], v[116:119], v[80:95]
	ds_read_b128 v[244:247], v151 offset:13824
	s_nop 2
	v_exp_f32_e32 v96, v96
	v_exp_f32_e32 v97, v97
	s_waitcnt lgkmcnt(4)
	v_mfma_f32_32x32x16_bf16 v[80:95], v[128:131], v[124:127], v[80:95]
	ds_read_b128 v[128:131], v151 offset:32
	v_exp_f32_e32 v98, v98
	v_exp_f32_e32 v99, v99
	v_exp_f32_e32 v100, v100
	v_mfma_f32_32x32x16_bf16 v[80:95], v[132:135], v[120:123], v[80:95]
	ds_read_b128 v[132:135], v151 offset:4640
	v_exp_f32_e32 v101, v101
	v_exp_f32_e32 v102, v102
	v_exp_f32_e32 v103, v103
	v_add_f32_e32 v167, v167, v96
	v_add_f32_e32 v190, v190, v97
	v_add_f32_e32 v191, v191, v98
	v_cvt_pk_bf16_f32 v176, v96, v97
	v_cvt_pk_bf16_f32 v177, v98, v99
	v_cvt_pk_bf16_f32 v178, v100, v101
	v_cvt_pk_bf16_f32 v179, v102, v103
	v_add_f32_e32 v196, v196, v99
	v_add_f32_e32 v167, v167, v100
	v_add_f32_e32 v190, v190, v101
	v_add_f32_e32 v191, v191, v102
	v_add_f32_e32 v196, v196, v103
	s_waitcnt lgkmcnt(4)
	v_mfma_f32_32x32x16_bf16 v[64:79], v[136:139], v[176:179], v[64:79]
	ds_read_b128 v[136:139], v151 offset:9248
	v_exp_f32_e32 v104, v104
	v_exp_f32_e32 v105, v105
	v_mfma_f32_32x32x16_bf16 v[48:63], v[152:155], v[176:179], v[48:63]
	ds_read_b128 v[152:155], v151 offset:13856
	v_exp_f32_e32 v106, v106
	v_exp_f32_e32 v107, v107
	v_cvt_pk_bf16_f32 v180, v104, v105
	s_waitcnt lgkmcnt(4)
	v_mfma_f32_32x32x16_bf16 v[32:47], v[224:227], v[176:179], v[32:47]
	ds_read_b128 v[224:227], v151 offset:64
	v_exp_f32_e32 v108, v108
	v_exp_f32_e32 v109, v109
	v_cvt_pk_bf16_f32 v181, v106, v107
	v_mfma_f32_32x32x16_bf16 v[0:15], v[244:247], v[176:179], v[0:15]
	ds_read_b128 v[244:247], v151 offset:4672
	v_exp_f32_e32 v110, v110
	v_exp_f32_e32 v111, v111
	v_cvt_pk_bf16_f32 v182, v108, v109
	v_cvt_pk_bf16_f32 v183, v110, v111
	s_nop 0
	s_waitcnt lgkmcnt(4)
	v_mfma_f32_32x32x16_bf16 v[64:79], v[128:131], v[180:183], v[64:79]
	ds_read_b128 v[128:131], v151 offset:9280
	v_exp_f32_e32 v80, v80
	v_exp_f32_e32 v81, v81
	v_mfma_f32_32x32x16_bf16 v[48:63], v[132:135], v[180:183], v[48:63]
	ds_read_b128 v[132:135], v151 offset:13888
	v_exp_f32_e32 v82, v82
	v_exp_f32_e32 v83, v83
	v_cvt_pk_bf16_f32 v184, v80, v81
	s_waitcnt lgkmcnt(4)
	v_mfma_f32_32x32x16_bf16 v[32:47], v[136:139], v[180:183], v[32:47]
	ds_read_b128 v[136:139], v151 offset:96
	v_exp_f32_e32 v84, v84
	v_exp_f32_e32 v85, v85
	v_cvt_pk_bf16_f32 v185, v82, v83
	v_mfma_f32_32x32x16_bf16 v[0:15], v[152:155], v[180:183], v[0:15]
	ds_read_b128 v[152:155], v151 offset:4704
	v_exp_f32_e32 v86, v86
	v_exp_f32_e32 v87, v87
	v_cvt_pk_bf16_f32 v186, v84, v85
	v_cvt_pk_bf16_f32 v187, v86, v87
	s_nop 0
	s_waitcnt lgkmcnt(4)
	v_mfma_f32_32x32x16_bf16 v[64:79], v[224:227], v[184:187], v[64:79]
	ds_read_b128 v[224:227], v151 offset:9312
	v_exp_f32_e32 v88, v88
	v_exp_f32_e32 v89, v89
	v_mfma_f32_32x32x16_bf16 v[48:63], v[244:247], v[184:187], v[48:63]
	ds_read_b128 v[244:247], v151 offset:13920
	v_exp_f32_e32 v90, v90
	v_exp_f32_e32 v91, v91
	v_cvt_pk_bf16_f32 v192, v88, v89
	s_waitcnt lgkmcnt(4)
	v_mfma_f32_32x32x16_bf16 v[32:47], v[128:131], v[184:187], v[32:47]
	v_exp_f32_e32 v92, v92
	v_exp_f32_e32 v93, v93
	v_cvt_pk_bf16_f32 v193, v90, v91
	s_waitcnt vmcnt(0)
	ds_write_b128 v168, v[228:231] offset:36864
	ds_write_b128 v168, v[232:235] offset:46080
	v_mfma_f32_32x32x16_bf16 v[0:15], v[132:135], v[184:187], v[0:15]
	v_exp_f32_e32 v94, v94
	v_exp_f32_e32 v95, v95
	v_cvt_pk_bf16_f32 v194, v92, v93
	v_cvt_pk_bf16_f32 v195, v94, v95
	s_nop 0
	ds_write_b64 v169, v[236:237] offset:55296
	ds_write_b64 v169, v[238:239] offset:55312
	s_waitcnt lgkmcnt(6)
	v_mfma_f32_32x32x16_bf16 v[64:79], v[136:139], v[192:195], v[64:79]
	v_add_f32_e32 v167, v167, v104
	v_add_f32_e32 v190, v190, v105
	v_add_f32_e32 v191, v191, v106
	v_add_f32_e32 v196, v196, v107
	ds_write_b64 v143, v[240:241] offset:55296
	ds_write_b64 v143, v[242:243] offset:55312
	v_mfma_f32_32x32x16_bf16 v[48:63], v[152:155], v[192:195], v[48:63]
	v_add_f32_e32 v167, v167, v108
	v_add_f32_e32 v190, v190, v109
	v_add_f32_e32 v191, v191, v110
	v_add_f32_e32 v196, v196, v111
	s_waitcnt lgkmcnt(6)
	v_mfma_f32_32x32x16_bf16 v[32:47], v[224:227], v[192:195], v[32:47]
	v_add_f32_e32 v167, v167, v80
	v_add_f32_e32 v190, v190, v81
	v_add_f32_e32 v191, v191, v82
	v_add_f32_e32 v196, v196, v83
	v_mfma_f32_32x32x16_bf16 v[0:15], v[244:247], v[192:195], v[0:15]
	v_add_f32_e32 v167, v167, v84
	v_add_f32_e32 v190, v190, v85
	v_add_f32_e32 v191, v191, v86
	v_add_f32_e32 v196, v196, v87
	s_waitcnt lgkmcnt(0)
	s_barrier
; #define MFMA(a, b, c) __builtin_amdgcn_mfma_f32_32x32x16_bf16((a), (b), (c), 0, 0, 0)
; DI void attn_item(const P& p, int l, int item, char* smem) {
;     ...
;     if (kt >= 0) {
;       const u16* Kc = Ks + (kt & 1) * (256 * 72);
;       const u16* Vc = Kc + 2 * 64 * 72;
;       bf16x8 kf[8];
; #pragma unroll
;       for (int i = 0; i < 8; ++i)
;         kf[i] = *(const bf16x8*)(Kc + (c * 64 + 32 * (i & 1) + li) * 72 + 16 * (i >> 1) + 8 * g);
;       u32x4 vf[16];
; #pragma unroll
;       for (int i = 0; i < 16; ++i) {
;         const int eb = i & 3, s = (i >> 2) & 1, kb = i >> 3;
;         vf[i] = *(const u32x4*)(Vc + (32 * eb + li) * 72 + 32 * kb + 16 * s + 8 * g);
;       }
;       f32x16 S[2];
; #pragma unroll
;       for (int kb = 0; kb < 2; ++kb)
; #pragma unroll
;         for (int r = 0; r < 16; ++r) S[kb][r] = negm;
; #pragma unroll
;       for (int i = 0; i < 8; ++i) S[i & 1] = MFMA(kf[i], qf[i >> 1], S[i & 1]);
;       u32x4 pk[4];
;       float sum = 0.f;
; #pragma unroll
;       for (int ch = 0; ch < 4; ++ch) {
;         const int kb = ch >> 1, s = ch & 1;
; #pragma unroll
;         for (int j2 = 0; j2 < 4; ++j2) {
;           const float p0 = __builtin_amdgcn_exp2f(S[kb][8 * s + 2 * j2]);
;           const float p1 = __builtin_amdgcn_exp2f(S[kb][8 * s + 2 * j2 + 1]);
;           sum += p0 + p1;
;           pk[ch][j2] = pack2(p0, p1);
;         }
;       }
;       ls += sum;
; #pragma unroll
;       for (int i = 0; i < 16; ++i) {
;         const int eb = i & 3, ch = i >> 2;
;         O[eb] = MFMA(__builtin_bit_cast(bf16x8, vf[i]), __builtin_bit_cast(bf16x8, pk[ch]), O[eb]);
;       }
;     }
;     __syncthreads();
	ds_read_b128 v[128:131], v150 offset:36864
	ds_read_b128 v[132:135], v150 offset:36896
	ds_read_b128 v[136:139], v150 offset:36928
	ds_read_b128 v[152:155], v150 offset:36960
	ds_read_b128 v[224:227], v150 offset:41472
	ds_read_b128 v[244:247], v150 offset:41504
	s_waitcnt lgkmcnt(4)
	v_mfma_f32_32x32x16_bf16 v[96:111], v[128:131], v[112:115], v[16:31]
	ds_read_b128 v[128:131], v150 offset:41536
	v_add_f32_e32 v167, v167, v88
	v_add_f32_e32 v190, v190, v89
	v_mfma_f32_32x32x16_bf16 v[96:111], v[132:135], v[116:119], v[96:111]
	ds_read_b128 v[132:135], v150 offset:41568
	v_add_f32_e32 v191, v191, v90
	v_add_f32_e32 v196, v196, v91
	s_waitcnt lgkmcnt(4)
	v_mfma_f32_32x32x16_bf16 v[96:111], v[136:139], v[124:127], v[96:111]
	ds_read_b128 v[136:139], v151 offset:36864
	v_add_f32_e32 v167, v167, v92
	v_add_f32_e32 v190, v190, v93
	v_mfma_f32_32x32x16_bf16 v[96:111], v[152:155], v[120:123], v[96:111]
	ds_read_b128 v[152:155], v151 offset:41472
	v_add_f32_e32 v191, v191, v94
	v_add_f32_e32 v196, v196, v95
	s_waitcnt lgkmcnt(4)
	v_mfma_f32_32x32x16_bf16 v[80:95], v[224:227], v[112:115], v[16:31]
	ds_read_b128 v[224:227], v151 offset:46080
	v_mfma_f32_32x32x16_bf16 v[80:95], v[244:247], v[116:119], v[80:95]
	ds_read_b128 v[244:247], v151 offset:50688
	s_nop 6
	v_exp_f32_e32 v96, v96
	v_exp_f32_e32 v97, v97
	s_waitcnt lgkmcnt(4)
	v_mfma_f32_32x32x16_bf16 v[80:95], v[128:131], v[124:127], v[80:95]
	ds_read_b128 v[128:131], v151 offset:36896
	v_exp_f32_e32 v98, v98
	v_exp_f32_e32 v99, v99
	v_exp_f32_e32 v100, v100
	v_mfma_f32_32x32x16_bf16 v[80:95], v[132:135], v[120:123], v[80:95]
	ds_read_b128 v[132:135], v151 offset:41504
	v_exp_f32_e32 v101, v101
	v_exp_f32_e32 v102, v102
	v_exp_f32_e32 v103, v103
	v_add_f32_e32 v167, v167, v96
	v_add_f32_e32 v190, v190, v97
	v_add_f32_e32 v191, v191, v98
	v_cvt_pk_bf16_f32 v176, v96, v97
	v_cvt_pk_bf16_f32 v177, v98, v99
	v_cvt_pk_bf16_f32 v178, v100, v101
	v_cvt_pk_bf16_f32 v179, v102, v103
	v_add_f32_e32 v196, v196, v99
	v_add_f32_e32 v167, v167, v100
	v_add_f32_e32 v190, v190, v101
	v_add_f32_e32 v191, v191, v102
	v_add_f32_e32 v196, v196, v103
	s_waitcnt lgkmcnt(4)
	v_mfma_f32_32x32x16_bf16 v[64:79], v[136:139], v[176:179], v[64:79]
	ds_read_b128 v[136:139], v151 offset:46112
	v_exp_f32_e32 v104, v104
	v_exp_f32_e32 v105, v105
	v_mfma_f32_32x32x16_bf16 v[48:63], v[152:155], v[176:179], v[48:63]
	ds_read_b128 v[152:155], v151 offset:50720
	v_exp_f32_e32 v106, v106
	v_exp_f32_e32 v107, v107
	v_cvt_pk_bf16_f32 v180, v104, v105
	s_waitcnt lgkmcnt(4)
	v_mfma_f32_32x32x16_bf16 v[32:47], v[224:227], v[176:179], v[32:47]
	ds_read_b128 v[224:227], v151 offset:36928
	v_exp_f32_e32 v108, v108
	v_exp_f32_e32 v109, v109
	v_cvt_pk_bf16_f32 v181, v106, v107
	v_mfma_f32_32x32x16_bf16 v[0:15], v[244:247], v[176:179], v[0:15]
	ds_read_b128 v[244:247], v151 offset:41536
	v_exp_f32_e32 v110, v110
	v_exp_f32_e32 v111, v111
	v_cvt_pk_bf16_f32 v182, v108, v109
	v_cvt_pk_bf16_f32 v183, v110, v111
	s_nop 0
	s_waitcnt lgkmcnt(4)
	v_mfma_f32_32x32x16_bf16 v[64:79], v[128:131], v[180:183], v[64:79]
	ds_read_b128 v[128:131], v151 offset:46144
	v_exp_f32_e32 v80, v80
	v_exp_f32_e32 v81, v81
	v_mfma_f32_32x32x16_bf16 v[48:63], v[132:135], v[180:183], v[48:63]
	ds_read_b128 v[132:135], v151 offset:50752
	v_exp_f32_e32 v82, v82
	v_exp_f32_e32 v83, v83
	v_cvt_pk_bf16_f32 v184, v80, v81
	s_waitcnt lgkmcnt(4)
	v_mfma_f32_32x32x16_bf16 v[32:47], v[136:139], v[180:183], v[32:47]
	ds_read_b128 v[136:139], v151 offset:36960
	v_exp_f32_e32 v84, v84
	v_exp_f32_e32 v85, v85
	v_cvt_pk_bf16_f32 v185, v82, v83
	v_mfma_f32_32x32x16_bf16 v[0:15], v[152:155], v[180:183], v[0:15]
	ds_read_b128 v[152:155], v151 offset:41568
	v_exp_f32_e32 v86, v86
	v_exp_f32_e32 v87, v87
	v_cvt_pk_bf16_f32 v186, v84, v85
	v_cvt_pk_bf16_f32 v187, v86, v87
	s_nop 0
	s_waitcnt lgkmcnt(4)
	v_mfma_f32_32x32x16_bf16 v[64:79], v[224:227], v[184:187], v[64:79]
	ds_read_b128 v[224:227], v151 offset:46176
	v_exp_f32_e32 v88, v88
	v_exp_f32_e32 v89, v89
	v_mfma_f32_32x32x16_bf16 v[48:63], v[244:247], v[184:187], v[48:63]
	ds_read_b128 v[244:247], v151 offset:50784
	v_exp_f32_e32 v90, v90
	v_exp_f32_e32 v91, v91
	v_cvt_pk_bf16_f32 v192, v88, v89
	s_waitcnt lgkmcnt(4)
	v_mfma_f32_32x32x16_bf16 v[32:47], v[128:131], v[184:187], v[32:47]
	v_exp_f32_e32 v92, v92
	v_exp_f32_e32 v93, v93
	v_cvt_pk_bf16_f32 v193, v90, v91
	v_mfma_f32_32x32x16_bf16 v[0:15], v[132:135], v[184:187], v[0:15]
	v_exp_f32_e32 v94, v94
	v_exp_f32_e32 v95, v95
	v_cvt_pk_bf16_f32 v194, v92, v93
	v_cvt_pk_bf16_f32 v195, v94, v95
	s_nop 0
	s_waitcnt lgkmcnt(2)
	v_mfma_f32_32x32x16_bf16 v[64:79], v[136:139], v[192:195], v[64:79]
	v_add_f32_e32 v167, v167, v104
	v_add_f32_e32 v190, v190, v105
	v_add_f32_e32 v191, v191, v106
	v_add_f32_e32 v196, v196, v107
	v_mfma_f32_32x32x16_bf16 v[48:63], v[152:155], v[192:195], v[48:63]
	v_add_f32_e32 v167, v167, v108
	v_add_f32_e32 v190, v190, v109
	v_add_f32_e32 v191, v191, v110
	v_add_f32_e32 v196, v196, v111
	s_waitcnt lgkmcnt(0)
	v_mfma_f32_32x32x16_bf16 v[32:47], v[224:227], v[192:195], v[32:47]
	v_add_f32_e32 v167, v167, v80
	v_add_f32_e32 v190, v190, v81
	v_add_f32_e32 v191, v191, v82
	v_add_f32_e32 v196, v196, v83
	v_mfma_f32_32x32x16_bf16 v[0:15], v[244:247], v[192:195], v[0:15]
	v_add_f32_e32 v167, v167, v84
	v_add_f32_e32 v190, v190, v85
	v_add_f32_e32 v191, v191, v86
	v_add_f32_e32 v196, v196, v87
	s_waitcnt lgkmcnt(0)
	s_barrier
; #define MFMA(a, b, c) __builtin_amdgcn_mfma_f32_32x32x16_bf16((a), (b), (c), 0, 0, 0)
; DI void attn_item(const P& p, int l, int item, char* smem) {
;     ...
;       for (int i = 0; i < 16; ++i) {
;         const int eb = i & 3, ch = i >> 2;
;         O[eb] = MFMA(__builtin_bit_cast(bf16x8, vf[i]), __builtin_bit_cast(bf16x8, pk[ch]), O[eb]);
;       }
;     }
;     __syncthreads();
;   }
;   const float lt = ls + __shfl_xor(ls, 32);
;   const float inv = (c == 0) ? (1.0f / lt) : (lam / lt);
;   float* exch = (float*)smem + qg * (64 * 64);
;   if (c == 1) {
; #pragma unroll
;     for (int eb = 0; eb < 4; ++eb)
; #pragma unroll
;       for (int r = 0; r < 16; ++r) exch[(eb * 16 + r) * 64 + lane] = O[eb][r] * inv;
;   }
;   __syncthreads();
;   if (c == 0) {
;     float ss = 0.f;
; #pragma unroll
;     for (int eb = 0; eb < 4; ++eb)
; #pragma unroll
;       for (int r = 0; r < 16; ++r) {
;         const float o = O[eb][r] * inv - exch[(eb * 16 + r) * 64 + lane];
;         O[eb][r] = o;
;         ss += o * o;
;       }
;     ss += __shfl_xor(ss, 32);
;     const float rn = rsqrtf(ss * (1.0f / 128.0f) + 1e-5f) * (1.0f - lam_init);
;     const size_t tok = (size_t)b * SEQ + tq;
; #pragma unroll
;     for (int eb = 0; eb < 4; ++eb)
; #pragma unroll
;       for (int rq = 0; rq < 4; ++rq) {
;         const int e = 32 * eb + 8 * rq + 4 * g;
;         const uint2 gt = *(const uint2*)(p.AG + tok * 512 + h * 128 + e);
;         const float4 sg = *(const float4*)(p.subg + l * 128 + e);
	v_add_f32_e32 v167, v167, v88
	v_add_f32_e32 v190, v190, v89
	v_add_f32_e32 v191, v191, v90
	v_add_f32_e32 v196, v196, v91
	v_add_f32_e32 v167, v167, v92
	v_add_f32_e32 v190, v190, v93
	v_add_f32_e32 v191, v191, v94
	v_add_f32_e32 v196, v196, v95
	v_add_f32_e32 v167, v167, v190
	v_add_f32_e32 v191, v191, v196
	v_readlane_b32 s6, v248, 5
	v_add_f32_e32 v96, v165, v166
	v_add_f32_e32 v97, v163, v164
	v_mul_f32_e32 v96, 0x3fb8aa3b, v96
	v_mul_f32_e32 v97, 0x3fb8aa3b, v97
	v_exp_f32_e32 v139, v96
	v_exp_f32_e32 v17, v97
	v_add_f32_e32 v16, v167, v191
	ds_bpermute_b32 v18, v158, v16
	v_sub_f32_e32 v17, v17, v139
	v_add_f32_e32 v17, s6, v17
	s_movk_i32 s6, 0x100
	v_cmp_gt_u32_e64 s[6:7], s6, v161
	s_waitcnt lgkmcnt(0)
	v_add_f32_e32 v16, v16, v18
	s_nop 0
	v_cndmask_b32_e64 v17, v17, 1.0, s[6:7]
	v_div_scale_f32 v18, s[10:11], v16, v16, v17
	v_rcp_f32_e32 v19, v18
	s_nop 0
	v_fma_f32 v24, -v18, v19, 1.0
	s_nop 0
	v_fmac_f32_e32 v19, v24, v19
	v_div_scale_f32 v24, vcc, v17, v16, v17
	v_mul_f32_e32 v25, v24, v19
	v_fma_f32 v26, -v18, v25, v24
	v_fmac_f32_e32 v25, v26, v19
	v_fma_f32 v18, -v18, v25, v24
	s_nop 0
	v_div_fmas_f32 v18, v18, v19, v25
	v_div_fixup_f32 v80, v18, v16, v17
	v_lshl_add_u32 v16, v162, 14, 0
	v_cmp_eq_u32_e32 vcc, 1, v160
	v_lshl_add_u32 v18, v141, 2, v16
	s_nop 0
	s_and_saveexec_b64 s[10:11], s[6:7]
	s_cbranch_execz .Lfin_nl
	v_and_b32_e32 v142, 15, v161
	v_bfe_u32 v143, v161, 4, 2
	v_and_b32_e32 v144, 0xffffffe0, v140
	v_add_u32_e32 v144, v144, v143
	s_lshl_b32 s56, s12, 11
	s_and_b32 s56, s56, 0x2000
	v_add_u32_e32 v144, s56, v144
	v_lshlrev_b32_e32 v144, 10, v144
	s_lshl_b32 s56, s95, 8
	s_and_b32 s56, s56, 0x300
	v_add_u32_e32 v144, s56, v144
	v_lshl_add_u32 v144, v142, 4, v144
	v_mov_b32_e32 v147, v144
	v_lshlrev_b32_e32 v145, 5, v142
	global_load_dwordx4 v[100:103], v145, s[30:31]
	global_load_dwordx4 v[104:107], v145, s[30:31] offset:16
	global_load_dwordx4 v[228:231], v144, s[44:45]
	v_add_u32_e32 v144, 0x1000, v144
	global_load_dwordx4 v[232:235], v144, s[44:45]
	v_add_u32_e32 v144, 0x1000, v144
	global_load_dwordx4 v[236:239], v144, s[44:45]
	v_add_u32_e32 v144, 0x1000, v144
	global_load_dwordx4 v[240:243], v144, s[44:45]
	v_add_u32_e32 v144, 0x1000, v144
	global_load_dwordx4 v[84:87], v144, s[44:45]
	v_add_u32_e32 v144, 0x1000, v144
	global_load_dwordx4 v[88:91], v144, s[44:45]
	v_add_u32_e32 v144, 0x1000, v144
	global_load_dwordx4 v[92:95], v144, s[44:45]
	v_add_u32_e32 v144, 0x1000, v144
	global_load_dwordx4 v[96:99], v144, s[44:45]
